# de-serialised epilogues: phase9 gain loads hoisted, phase5 residual loads 4-deep pipelined with counted vmcnt, passC bonus scalars fetched by one early load
# speedup vs baseline: 1.0360x; 1.0078x over previous
.LBB0_1227:
	v_and_b32_e32 v24, -4, v57
	v_and_b32_e32 v36, 15, v53
	v_add_u32_e32 v27, s59, v24
	v_or_b32_e32 v38, s56, v36
	v_lshlrev_b32_e32 v34, 6, v27
	s_waitcnt vmcnt(0)
	v_or_b32_e32 v32, 0x1000, v38
	v_add_u32_e32 v24, v34, v32
	v_or_b32_e32 v40, 64, v34
	v_or_b32_e32 v41, 0x80, v34
	v_or_b32_e32 v42, 0xc0, v34
	v_or_b32_e32 v43, 0x1010, v38
	v_ashrrev_i32_e32 v25, 31, v24
	v_add_u32_e32 v28, v40, v32
	v_add_u32_e32 v30, v41, v32
	v_add_u32_e32 v32, v42, v32
	v_add_u32_e32 v34, v34, v43
	v_lshl_add_u64 v[24:25], v[24:25], 1, s[42:43]
	v_ashrrev_i32_e32 v29, 31, v28
	v_ashrrev_i32_e32 v31, 31, v30
	v_ashrrev_i32_e32 v33, 31, v32
	v_ashrrev_i32_e32 v35, 31, v34
	v_lshl_add_u64 v[28:29], v[28:29], 1, s[42:43]
	v_lshl_add_u64 v[30:31], v[30:31], 1, s[42:43]
	v_lshl_add_u64 v[32:33], v[32:33], 1, s[42:43]
	v_lshl_add_u64 v[34:35], v[34:35], 1, s[42:43]
	global_load_ushort v50, v[24:25], off
	global_load_ushort v54, v[28:29], off
	global_load_ushort v67, v[30:31], off
	global_load_ushort v70, v[32:33], off
	global_load_ushort v71, v[34:35], off
	v_add_u32_e32 v24, v40, v43
	v_ashrrev_i32_e32 v25, 31, v24
	v_add_u32_e32 v28, v41, v43
	v_add_u32_e32 v30, v42, v43
	v_lshl_add_u64 v[24:25], v[24:25], 1, s[42:43]
	v_ashrrev_i32_e32 v29, 31, v28
	v_ashrrev_i32_e32 v31, 31, v30
	v_lshl_add_u64 v[28:29], v[28:29], 1, s[42:43]
	v_lshl_add_u64 v[30:31], v[30:31], 1, s[42:43]
	global_load_ushort v25, v[24:25], off
	s_nop 0
	global_load_ushort v72, v[28:29], off
	global_load_ushort v73, v[30:31], off
	v_ashrrev_i32_e32 v24, 1, v53
	v_and_b32_e32 v28, -8, v24
	v_or_b32_e32 v74, s59, v36
	v_lshlrev_b32_e32 v24, 2, v28
	v_lshlrev_b32_e32 v29, 2, v36
	v_mul_lo_u32 v28, v28, s62
	v_add3_u32 v36, s16, v28, v29
	v_add_u32_e32 v44, 0x4000, v36
	v_add_u32_e32 v68, 0x4800, v36
	v_lshl_add_u32 v27, v27, 6, v27
	s_mov_b32 s4, 0
	s_mov_b32 s5, s80
	s_waitcnt vmcnt(2)
	v_mad_u64_u32 v[48:49], s[0:1], v74, s62, v[24:25]
	ds_read2_b32 v[28:29], v48 offset1:1
	ds_read2_b32 v[30:31], v48 offset0:2 offset1:3
	ds_read2_b32 v[32:33], v48 offset0:4 offset1:5
	ds_read2_b32 v[34:35], v48 offset0:6 offset1:7
	v_add_u32_e32 v49, 0x4400, v36
	ds_read2_b32 v[60:61], v48 offset0:32 offset1:33
	ds_read2_b32 v[40:41], v44 offset0:64 offset1:80
	ds_read2_b32 v[42:43], v44 offset0:129 offset1:145
	ds_read2_b32 v[44:45], v44 offset0:194 offset1:210
	ds_read2_b32 v[46:47], v49 offset0:3 offset1:19
	ds_read2_b32 v[56:57], v49 offset0:68 offset1:84
	ds_read2_b32 v[58:59], v49 offset0:133 offset1:149
	ds_read2_b32 v[62:63], v49 offset0:198 offset1:214
	ds_read2_b32 v[68:69], v68 offset0:7 offset1:23
	s_waitcnt lgkmcnt(12)
	v_cvt_pk_bf16_f32 v28, v28, v29
	s_waitcnt lgkmcnt(11)
	v_cvt_pk_bf16_f32 v29, v30, v31
	s_waitcnt lgkmcnt(10)
	v_cvt_pk_bf16_f32 v30, v32, v33
	s_waitcnt lgkmcnt(9)
	v_cvt_pk_bf16_f32 v31, v34, v35
	s_waitcnt lgkmcnt(6)
	v_cvt_pk_bf16_f32 v32, v40, v42
	v_cvt_pk_bf16_f32 v40, v41, v43
	s_waitcnt lgkmcnt(4)
	v_cvt_pk_bf16_f32 v33, v44, v46
	v_cvt_pk_bf16_f32 v41, v45, v47
	s_waitcnt lgkmcnt(2)
	v_cvt_pk_bf16_f32 v34, v56, v58
	v_cvt_pk_bf16_f32 v42, v57, v59
	s_waitcnt lgkmcnt(0)
	v_cvt_pk_bf16_f32 v35, v62, v68
	v_cvt_pk_bf16_f32 v43, v63, v69
	v_lshlrev_b32_e32 v44, 16, v50
	v_lshlrev_b32_e32 v45, 16, v54
	v_lshlrev_b32_e32 v46, 16, v67
	v_lshlrev_b32_e32 v47, 16, v70
	v_lshlrev_b32_e32 v56, 16, v71
	v_lshlrev_b32_e32 v57, 16, v25
	s_waitcnt vmcnt(1)
	v_lshlrev_b32_e32 v58, 16, v72
	s_waitcnt vmcnt(0)
	v_lshlrev_b32_e32 v59, 16, v73
	v_add_u32_e32 v25, 0x6000, v36
	v_mfma_f32_16x16x32_bf16 v[32:35], v[28:31], v[32:35], v[44:47]
	v_mfma_f32_16x16x32_bf16 v[28:31], v[28:31], v[40:43], v[56:59]
	s_nop 1
	ds_read2_b32 v[44:45], v25 offset0:96 offset1:112
	ds_read2_b32 v[46:47], v25 offset0:161 offset1:177
	ds_read2_b32 v[42:43], v48 offset0:34 offset1:35
	ds_read2_b32 v[56:57], v48 offset0:36 offset1:37
	ds_read2_b32 v[48:49], v48 offset0:38 offset1:39
	ds_read2_b32 v[58:59], v25 offset0:226 offset1:242
	v_add_u32_e32 v25, 0x6400, v36
	v_cvt_pk_bf16_f32 v40, v60, v61
	ds_read2_b32 v[60:61], v25 offset0:35 offset1:51
	ds_read2_b32 v[62:63], v25 offset0:100 offset1:116
	ds_read2_b32 v[68:69], v25 offset0:165 offset1:181
	ds_read2_b32 v[70:71], v25 offset0:230 offset1:246
	v_add_u32_e32 v25, 0x6800, v36
	ds_read2_b32 v[72:73], v25 offset0:39 offset1:55
	s_waitcnt lgkmcnt(8)
	v_cvt_pk_bf16_f32 v41, v42, v43
	s_waitcnt lgkmcnt(7)
	v_cvt_pk_bf16_f32 v42, v56, v57
	s_waitcnt lgkmcnt(6)
	v_cvt_pk_bf16_f32 v43, v48, v49
	v_cvt_pk_bf16_f32 v44, v44, v46
	v_cvt_pk_bf16_f32 v56, v45, v47
	s_waitcnt lgkmcnt(4)
	v_cvt_pk_bf16_f32 v45, v58, v60
	s_waitcnt lgkmcnt(2)
	v_cvt_pk_bf16_f32 v46, v62, v68
	s_waitcnt lgkmcnt(0)
	v_cvt_pk_bf16_f32 v47, v70, v72
	v_cvt_pk_bf16_f32 v57, v59, v61
	v_cvt_pk_bf16_f32 v58, v63, v69
	v_mfma_f32_16x16x32_bf16 v[32:35], v[40:43], v[44:47], v[32:35]
	v_cvt_pk_bf16_f32 v59, v71, v73
	v_add_lshl_u32 v36, v27, v38, 2
	v_add_u32_e32 v25, 0x8200, v36
	v_mfma_f32_16x16x32_bf16 v[28:31], v[40:43], v[56:59], v[28:31]
	v_or_b32_e32 v49, 16, v38
	s_nop 2
	ds_write2_b32 v25, v33, v34 offset0:65 offset1:130
	ds_write_b32 v36, v35 offset:34060
	v_add_u32_e32 v25, 0x8000, v36
	v_add_lshl_u32 v50, v27, v49, 2
	ds_write2_b32 v25, v32, v28 offset0:128 offset1:144
	v_add_u32_e32 v25, 0x8200, v50
	ds_write2_b32 v25, v29, v30 offset0:65 offset1:130
	ds_write_b32 v50, v31 offset:34060
	v_mad_u64_u32 v[24:25], s[0:1], v74, s65, v[24:25]
	ds_read_b128 v[28:31], v24 offset:49920
	ds_read_b128 v[32:35], v24 offset:49936
	ds_read_b128 v[40:43], v24 offset:50048
	ds_read_b128 v[44:47], v24 offset:50064
	ds_read_b128 v[56:59], v24 offset:50192
	s_waitcnt lgkmcnt(4)
	v_cvt_pk_bf16_f32 v28, v28, v29
	v_cvt_pk_bf16_f32 v29, v30, v31
	s_waitcnt lgkmcnt(3)
	v_cvt_pk_bf16_f32 v30, v32, v33
	v_cvt_pk_bf16_f32 v31, v34, v35
	s_waitcnt lgkmcnt(2)
	v_cvt_pk_bf16_f32 v40, v40, v41
	v_cvt_pk_bf16_f32 v41, v42, v43
	s_waitcnt lgkmcnt(1)
	v_cvt_pk_bf16_f32 v42, v44, v45
	v_cvt_pk_bf16_f32 v43, v46, v47
	ds_read_b128 v[44:47], v24 offset:50176
	v_mfma_f32_16x16x32_bf16 v[32:35], v[28:31], v[0:3], 0
	v_add_u32_e32 v25, 0x41, v27
	v_add_u32_e32 v54, v25, v38
	v_add_u32_e32 v24, 0x82, v27
	v_mfma_f32_16x16x32_bf16 v[28:31], v[28:31], v[4:7], 0
	s_waitcnt lgkmcnt(0)
	v_cvt_pk_bf16_f32 v44, v44, v45
	v_cvt_pk_bf16_f32 v45, v46, v47
	v_cvt_pk_bf16_f32 v46, v56, v57
	v_cvt_pk_bf16_f32 v47, v58, v59
	v_mfma_f32_16x16x32_bf16 v[32:35], v[40:43], v[8:11], v[32:35]
	v_add_u32_e32 v36, 0x18600, v36
	v_add_u32_e32 v27, 0xc3, v27
	v_add_u32_e32 v48, s71, v53
	v_mfma_f32_16x16x32_bf16 v[28:31], v[40:43], v[12:15], v[28:31]
	v_add_u32_e32 v40, v24, v38
	v_add_u32_e32 v38, v27, v38
	v_add_u32_e32 v24, v24, v49
	v_mfma_f32_16x16x32_bf16 v[32:35], v[44:47], v[16:19], v[32:35]
	v_add_u32_e32 v25, v25, v49
	v_add_u32_e32 v27, v27, v49
	v_lshl_add_u32 v24, v24, 2, v66
	v_mfma_f32_16x16x32_bf16 v[28:31], v[44:47], v[20:23], v[28:31]
	s_lshl_b32 s0, s70, 2
	s_nop 2
	ds_write_b32 v36, v32
	v_lshl_add_u32 v32, v54, 2, v66
	ds_write_b32 v32, v33
	v_lshl_add_u32 v32, v40, 2, v66
	ds_write_b32 v32, v34
	v_lshl_add_u32 v32, v38, 2, v66
	ds_write_b32 v32, v35
	v_lshl_add_u32 v25, v25, 2, v66
	ds_write_b32 v24, v30
	v_lshl_add_u32 v24, v27, 2, v66
	s_add_u32 s0, s60, s0
	v_ashrrev_i32_e32 v49, 31, v48
	v_add_u32_e32 v32, 0x18600, v50
	ds_write_b32 v25, v29
	ds_write_b32 v24, v31
	s_addc_u32 s1, s61, 0
	v_lshl_add_u64 v[24:25], v[48:49], 1, s[28:29]
	v_lshl_add_u32 v27, v53, 2, s33
	v_and_b32_e32 v101, 7, v53
	s_add_i32 s12, s68, s80
	v_lshl_add_u32 v101, v101, 3, s12
	s_add_i32 s12, s68, s69
	s_add_i32 s12, s12, -1
	v_min_u32_e32 v101, s12, v101
	v_lshlrev_b32_e32 v101, 5, v101
	global_load_dword v100, v101, s[0:1]
	ds_write_b32 v32, v28
	s_waitcnt lgkmcnt(0)
	s_barrier
	s_waitcnt vmcnt(0)
	s_branch .LBB0_1229

.LBB0_1229:
	v_add_u32_e32 v28, s4, v27
	ds_read_b32 v29, v28 offset:33280
	s_cmp_ge_u32 s5, s69
	s_waitcnt lgkmcnt(0)
	v_add_f32_dpp v30, v29, v29 quad_perm:[1,0,3,2] row_mask:0xf bank_mask:0xf bound_ctrl:1
	s_nop 1
	v_add_f32_dpp v30, v30, v30 quad_perm:[2,3,0,1] row_mask:0xf bank_mask:0xf bound_ctrl:1
	s_nop 1
	v_add_f32_dpp v30, v30, v30 row_half_mirror row_mask:0xf bank_mask:0xf bound_ctrl:1
	s_nop 1
	v_add_f32_dpp v30, v30, v30 row_mirror row_mask:0xf bank_mask:0xf bound_ctrl:1
	s_nop 0
	v_readlane_b32 s7, v30, 16
	v_readlane_b32 s6, v30, 0
	v_readlane_b32 s8, v30, 32
	v_readlane_b32 s9, v30, 48
	v_mov_b32_e32 v30, s7
	v_add_f32_e32 v30, s6, v30
	v_add_f32_e32 v30, s8, v30
	v_add_f32_e32 v30, s9, v30
	v_fmac_f32_e32 v29, 0xbc800000, v30
	v_mul_f32_e32 v30, v29, v29
	s_nop 1
	v_mov_b32_dpp v30, v30 quad_perm:[1,0,3,2] row_mask:0xf bank_mask:0xf bound_ctrl:1
	v_fmac_f32_e32 v30, v29, v29
	s_nop 1
	v_add_f32_dpp v30, v30, v30 quad_perm:[2,3,0,1] row_mask:0xf bank_mask:0xf bound_ctrl:1
	s_nop 1
	v_add_f32_dpp v30, v30, v30 row_half_mirror row_mask:0xf bank_mask:0xf bound_ctrl:1
	s_nop 1
	v_add_f32_dpp v30, v30, v30 row_mirror row_mask:0xf bank_mask:0xf bound_ctrl:1
	s_nop 0
	v_readlane_b32 s6, v30, 0
	v_readlane_b32 s9, v30, 16
	v_readlane_b32 s7, v30, 32
	v_readlane_b32 s8, v30, 48
	s_cbranch_scc1 .LBB0_1231
	s_add_i32 s10, s68, s5
	s_ashr_i32 s11, s10, 31
	s_sub_i32 s12, s5, s80
	s_lshr_b32 s12, s12, 3
	v_readlane_b32 s12, v100, s12
	s_nop 1
	v_mov_b32_e32 v53, s12
	v_mov_b32_e32 v30, s9
	v_add_f32_e32 v30, s6, v30
	v_add_f32_e32 v30, s7, v30
	v_add_f32_e32 v30, s8, v30
	v_fmamk_f32 v30, v30, 0x3c800000, v51
	v_mul_f32_e32 v33, 0x4b800000, v30
	v_cmp_gt_f32_e32 vcc, s66, v30
	v_add_u32_e32 v31, 0x18600, v28
	v_add_u32_e32 v32, 0x14500, v28
	v_cndmask_b32_e32 v30, v30, v33, vcc
	v_rsq_f32_e32 v30, v30
	ds_read_b32 v33, v31
	ds_read_b32 v31, v32
	s_lshl_b64 s[6:7], s[10:11], 11
	v_mul_f32_e32 v32, 0x45800000, v30
	v_cndmask_b32_e32 v30, v30, v32, vcc
	v_mul_f32_e32 v30, v29, v30
	s_waitcnt lgkmcnt(0)
	v_pk_mul_f32 v[30:31], v[52:53], v[30:31]
	s_nop 0
	v_add_f32_e32 v29, v37, v30
	v_add_f32_e32 v29, v29, v31
	v_mul_f32_e32 v29, v33, v29
	v_cvt_pk_bf16_f32 v29, v29, s0
	v_lshl_add_u64 v[30:31], v[24:25], 0, s[6:7]
	global_store_short v[30:31], v29, off
.LBB0_1231:
	ds_read_b32 v29, v28 offset:35360
	s_add_i32 s8, s5, 8
	s_cmp_ge_u32 s8, s69
	s_waitcnt lgkmcnt(0)
	v_add_f32_dpp v30, v29, v29 quad_perm:[1,0,3,2] row_mask:0xf bank_mask:0xf bound_ctrl:1
	s_nop 1
	v_add_f32_dpp v30, v30, v30 quad_perm:[2,3,0,1] row_mask:0xf bank_mask:0xf bound_ctrl:1
	s_nop 1
	v_add_f32_dpp v30, v30, v30 row_half_mirror row_mask:0xf bank_mask:0xf bound_ctrl:1
	s_nop 1
	v_add_f32_dpp v30, v30, v30 row_mirror row_mask:0xf bank_mask:0xf bound_ctrl:1
	s_nop 0
	v_readlane_b32 s7, v30, 16
	v_readlane_b32 s6, v30, 0
	v_readlane_b32 s9, v30, 32
	v_readlane_b32 s10, v30, 48
	v_mov_b32_e32 v30, s7
	v_add_f32_e32 v30, s6, v30
	v_add_f32_e32 v30, s9, v30
	v_add_f32_e32 v30, s10, v30
	v_fmac_f32_e32 v29, 0xbc800000, v30
	v_mul_f32_e32 v30, v29, v29
	s_nop 1
	v_mov_b32_dpp v30, v30 quad_perm:[1,0,3,2] row_mask:0xf bank_mask:0xf bound_ctrl:1
	v_fmac_f32_e32 v30, v29, v29
	s_nop 1
	v_add_f32_dpp v30, v30, v30 quad_perm:[2,3,0,1] row_mask:0xf bank_mask:0xf bound_ctrl:1
	s_nop 1
	v_add_f32_dpp v30, v30, v30 row_half_mirror row_mask:0xf bank_mask:0xf bound_ctrl:1
	s_nop 1
	v_add_f32_dpp v30, v30, v30 row_mirror row_mask:0xf bank_mask:0xf bound_ctrl:1
	s_nop 0
	v_readlane_b32 s6, v30, 0
	v_readlane_b32 s9, v30, 16
	v_readlane_b32 s7, v30, 32
	v_readlane_b32 s8, v30, 48
	s_cbranch_scc1 .LBB0_1228
	s_add_i32 s10, s68, s5
	s_add_i32 s10, s10, 8
	s_ashr_i32 s11, s10, 31
	s_sub_i32 s12, s5, s80
	s_lshr_b32 s12, s12, 3
	s_add_i32 s12, s12, 1
	v_readlane_b32 s12, v100, s12
	s_nop 1
	v_mov_b32_e32 v53, s12
	v_mov_b32_e32 v30, s9
	v_add_f32_e32 v30, s6, v30
	v_add_f32_e32 v30, s7, v30
	v_add_f32_e32 v30, s8, v30
	v_fmamk_f32 v30, v30, 0x3c800000, v51
	v_mul_f32_e32 v32, 0x4b800000, v30
	v_cmp_gt_f32_e32 vcc, s66, v30
	v_add_u32_e32 v31, 0x18e20, v28
	v_add_u32_e32 v28, 0x14d20, v28
	v_cndmask_b32_e32 v30, v30, v32, vcc
	v_rsq_f32_e32 v30, v30
	ds_read_b32 v32, v31
	ds_read_b32 v31, v28
	s_lshl_b64 s[6:7], s[10:11], 11
	v_mul_f32_e32 v28, 0x45800000, v30
	v_cndmask_b32_e32 v28, v30, v28, vcc
	v_mul_f32_e32 v30, v29, v28
	s_waitcnt lgkmcnt(0)
	v_pk_mul_f32 v[28:29], v[52:53], v[30:31]
	s_nop 0
	v_add_f32_e32 v28, v37, v28
	v_add_f32_e32 v28, v28, v29
	v_mul_f32_e32 v28, v32, v28
	v_cvt_pk_bf16_f32 v30, v28, s0
	v_lshl_add_u64 v[28:29], v[24:25], 0, s[6:7]
	global_store_short v[28:29], v30, off
	s_branch .LBB0_1228

.LBB0_1394:
	v_and_b32_e32 v24, -4, v59
	v_and_b32_e32 v34, 15, v53
	v_add_u32_e32 v27, s59, v24
	v_or_b32_e32 v40, s56, v34
	s_waitcnt vmcnt(0)
	v_lshlrev_b32_e32 v36, 6, v27
	v_or_b32_e32 v32, 0x1000, v40
	v_add_u32_e32 v24, v36, v32
	v_or_b32_e32 v38, 64, v36
	v_or_b32_e32 v39, 0x80, v36
	v_or_b32_e32 v42, 0xc0, v36
	v_or_b32_e32 v43, 0x1010, v40
	v_ashrrev_i32_e32 v25, 31, v24
	v_add_u32_e32 v28, v38, v32
	v_add_u32_e32 v30, v39, v32
	v_add_u32_e32 v32, v42, v32
	v_add_u32_e32 v36, v36, v43
	v_lshl_add_u64 v[24:25], v[24:25], 1, s[42:43]
	v_ashrrev_i32_e32 v29, 31, v28
	v_ashrrev_i32_e32 v31, 31, v30
	v_ashrrev_i32_e32 v33, 31, v32
	v_ashrrev_i32_e32 v37, 31, v36
	v_lshl_add_u64 v[28:29], v[28:29], 1, s[42:43]
	v_lshl_add_u64 v[30:31], v[30:31], 1, s[42:43]
	v_lshl_add_u64 v[32:33], v[32:33], 1, s[42:43]
	v_lshl_add_u64 v[36:37], v[36:37], 1, s[42:43]
	global_load_ushort v50, v[24:25], off
	global_load_ushort v54, v[28:29], off
	global_load_ushort v67, v[30:31], off
	global_load_ushort v70, v[32:33], off
	global_load_ushort v71, v[36:37], off
	v_add_u32_e32 v24, v38, v43
	v_ashrrev_i32_e32 v25, 31, v24
	v_add_u32_e32 v28, v39, v43
	v_add_u32_e32 v30, v42, v43
	v_lshl_add_u64 v[24:25], v[24:25], 1, s[42:43]
	v_ashrrev_i32_e32 v29, 31, v28
	v_ashrrev_i32_e32 v31, 31, v30
	v_lshl_add_u64 v[28:29], v[28:29], 1, s[42:43]
	v_lshl_add_u64 v[30:31], v[30:31], 1, s[42:43]
	global_load_ushort v25, v[24:25], off
	s_nop 0
	global_load_ushort v72, v[28:29], off
	global_load_ushort v73, v[30:31], off
	v_ashrrev_i32_e32 v24, 1, v53
	v_and_b32_e32 v28, -8, v24
	v_or_b32_e32 v74, s59, v34
	v_lshlrev_b32_e32 v24, 2, v28
	v_lshlrev_b32_e32 v29, 2, v34
	v_mul_lo_u32 v28, v28, s62
	v_add3_u32 v34, s16, v28, v29
	v_add_u32_e32 v62, 0x4400, v34
	v_add_u32_e32 v68, 0x4800, v34
	v_lshl_add_u32 v27, v27, 6, v27
	s_waitcnt vmcnt(2)
	v_mad_u64_u32 v[32:33], s[0:1], v74, s62, v[24:25]
	ds_read2_b32 v[28:29], v32 offset1:1
	ds_read2_b32 v[30:31], v32 offset0:2 offset1:3
	ds_read2_b32 v[36:37], v32 offset0:4 offset1:5
	ds_read2_b32 v[38:39], v32 offset0:6 offset1:7
	v_add_u32_e32 v33, 0x4000, v34
	ds_read2_b32 v[60:61], v32 offset0:32 offset1:33
	ds_read2_b32 v[42:43], v33 offset0:64 offset1:80
	ds_read2_b32 v[44:45], v33 offset0:129 offset1:145
	ds_read2_b32 v[46:47], v33 offset0:194 offset1:210
	ds_read2_b32 v[48:49], v62 offset0:3 offset1:19
	ds_read2_b32 v[56:57], v62 offset0:68 offset1:84
	ds_read2_b32 v[58:59], v62 offset0:133 offset1:149
	ds_read2_b32 v[62:63], v62 offset0:198 offset1:214
	ds_read2_b32 v[68:69], v68 offset0:7 offset1:23
	s_waitcnt lgkmcnt(12)
	v_cvt_pk_bf16_f32 v28, v28, v29
	s_waitcnt lgkmcnt(11)
	v_cvt_pk_bf16_f32 v29, v30, v31
	s_waitcnt lgkmcnt(10)
	v_cvt_pk_bf16_f32 v30, v36, v37
	s_waitcnt lgkmcnt(9)
	v_cvt_pk_bf16_f32 v31, v38, v39
	s_waitcnt lgkmcnt(6)
	v_cvt_pk_bf16_f32 v36, v42, v44
	v_cvt_pk_bf16_f32 v42, v43, v45
	s_waitcnt lgkmcnt(4)
	v_cvt_pk_bf16_f32 v37, v46, v48
	v_cvt_pk_bf16_f32 v43, v47, v49
	s_waitcnt lgkmcnt(2)
	v_cvt_pk_bf16_f32 v38, v56, v58
	v_cvt_pk_bf16_f32 v44, v57, v59
	s_waitcnt lgkmcnt(0)
	v_cvt_pk_bf16_f32 v39, v62, v68
	v_cvt_pk_bf16_f32 v45, v63, v69
	v_lshlrev_b32_e32 v46, 16, v50
	v_lshlrev_b32_e32 v47, 16, v54
	v_lshlrev_b32_e32 v48, 16, v67
	v_lshlrev_b32_e32 v49, 16, v70
	v_lshlrev_b32_e32 v56, 16, v71
	v_lshlrev_b32_e32 v57, 16, v25
	s_waitcnt vmcnt(1)
	v_lshlrev_b32_e32 v58, 16, v72
	s_waitcnt vmcnt(0)
	v_lshlrev_b32_e32 v59, 16, v73
	v_add_u32_e32 v25, 0x6000, v34
	v_mfma_f32_16x16x32_bf16 v[36:39], v[28:31], v[36:39], v[46:49]
	v_mfma_f32_16x16x32_bf16 v[28:31], v[28:31], v[42:45], v[56:59]
	s_nop 1
	ds_read2_b32 v[46:47], v25 offset0:96 offset1:112
	ds_read2_b32 v[48:49], v25 offset0:161 offset1:177
	ds_read2_b32 v[44:45], v32 offset0:34 offset1:35
	ds_read2_b32 v[56:57], v32 offset0:36 offset1:37
	ds_read2_b32 v[32:33], v32 offset0:38 offset1:39
	ds_read2_b32 v[58:59], v25 offset0:226 offset1:242
	v_add_u32_e32 v25, 0x6400, v34
	v_cvt_pk_bf16_f32 v42, v60, v61
	ds_read2_b32 v[60:61], v25 offset0:35 offset1:51
	ds_read2_b32 v[62:63], v25 offset0:100 offset1:116
	ds_read2_b32 v[68:69], v25 offset0:165 offset1:181
	ds_read2_b32 v[70:71], v25 offset0:230 offset1:246
	v_add_u32_e32 v25, 0x6800, v34
	ds_read2_b32 v[72:73], v25 offset0:39 offset1:55
	s_waitcnt lgkmcnt(8)
	v_cvt_pk_bf16_f32 v43, v44, v45
	s_waitcnt lgkmcnt(7)
	v_cvt_pk_bf16_f32 v44, v56, v57
	s_waitcnt lgkmcnt(6)
	v_cvt_pk_bf16_f32 v45, v32, v33
	v_cvt_pk_bf16_f32 v46, v46, v48
	v_cvt_pk_bf16_f32 v56, v47, v49
	s_waitcnt lgkmcnt(4)
	v_cvt_pk_bf16_f32 v47, v58, v60
	s_waitcnt lgkmcnt(2)
	v_cvt_pk_bf16_f32 v48, v62, v68
	s_waitcnt lgkmcnt(0)
	v_cvt_pk_bf16_f32 v49, v70, v72
	v_cvt_pk_bf16_f32 v57, v59, v61
	v_cvt_pk_bf16_f32 v58, v63, v69
	v_mfma_f32_16x16x32_bf16 v[36:39], v[42:45], v[46:49], v[36:39]
	v_cvt_pk_bf16_f32 v59, v71, v73
	v_add_lshl_u32 v33, v27, v40, 2
	v_add_u32_e32 v25, 0x8200, v33
	v_mfma_f32_16x16x32_bf16 v[28:31], v[42:45], v[56:59], v[28:31]
	v_or_b32_e32 v34, 16, v40
	s_nop 2
	ds_write2_b32 v25, v37, v38 offset0:65 offset1:130
	ds_write_b32 v33, v39 offset:34060
	v_add_u32_e32 v25, 0x8000, v33
	v_add_lshl_u32 v50, v27, v34, 2
	ds_write2_b32 v25, v36, v28 offset0:128 offset1:144
	v_add_u32_e32 v25, 0x8200, v50
	ds_write2_b32 v25, v29, v30 offset0:65 offset1:130
	ds_write_b32 v50, v31 offset:34060
	v_mad_u64_u32 v[24:25], s[0:1], v74, s69, v[24:25]
	ds_read_b128 v[28:31], v24 offset:49920
	ds_read_b128 v[36:39], v24 offset:49936
	ds_read_b128 v[42:45], v24 offset:50048
	ds_read_b128 v[46:49], v24 offset:50064
	ds_read_b128 v[56:59], v24 offset:50192
	s_waitcnt lgkmcnt(4)
	v_cvt_pk_bf16_f32 v28, v28, v29
	v_cvt_pk_bf16_f32 v29, v30, v31
	s_waitcnt lgkmcnt(3)
	v_cvt_pk_bf16_f32 v30, v36, v37
	v_cvt_pk_bf16_f32 v31, v38, v39
	s_waitcnt lgkmcnt(2)
	v_cvt_pk_bf16_f32 v42, v42, v43
	v_cvt_pk_bf16_f32 v43, v44, v45
	s_waitcnt lgkmcnt(1)
	v_cvt_pk_bf16_f32 v44, v46, v47
	v_cvt_pk_bf16_f32 v45, v48, v49
	ds_read_b128 v[46:49], v24 offset:50176
	v_mfma_f32_16x16x32_bf16 v[36:39], v[28:31], v[0:3], 0
	v_add_u32_e32 v25, 0x41, v27
	v_add_u32_e32 v54, v25, v40
	v_add_u32_e32 v24, 0x82, v27
	s_waitcnt lgkmcnt(0)
	v_cvt_pk_bf16_f32 v46, v46, v47
	v_cvt_pk_bf16_f32 v47, v48, v49
	v_cvt_pk_bf16_f32 v48, v56, v57
	v_cvt_pk_bf16_f32 v49, v58, v59
	v_mfma_f32_16x16x32_bf16 v[28:31], v[28:31], v[4:7], 0
	v_add_u32_e32 v33, 0x18600, v33
	v_add_u32_e32 v27, 0xc3, v27
	v_add_u32_e32 v32, s55, v53
	v_mfma_f32_16x16x32_bf16 v[36:39], v[42:45], v[8:11], v[36:39]
	v_add_u32_e32 v25, v25, v34
	v_lshl_add_u32 v25, v25, 2, v66
	s_mov_b32 s0, 0
	v_mfma_f32_16x16x32_bf16 v[28:31], v[42:45], v[12:15], v[28:31]
	v_add_u32_e32 v42, v24, v40
	v_add_u32_e32 v40, v27, v40
	v_add_u32_e32 v24, v24, v34
	v_mfma_f32_16x16x32_bf16 v[36:39], v[46:49], v[16:19], v[36:39]
	v_add_u32_e32 v27, v27, v34
	v_lshl_add_u32 v24, v24, 2, v66
	s_mov_b32 s1, s80
	v_mfma_f32_16x16x32_bf16 v[28:31], v[46:49], v[20:23], v[28:31]
	s_nop 3
	ds_write_b32 v33, v36
	v_lshl_add_u32 v33, v54, 2, v66
	ds_write_b32 v33, v37
	v_lshl_add_u32 v33, v42, 2, v66
	ds_write_b32 v33, v38
	v_lshl_add_u32 v33, v40, 2, v66
	ds_write_b32 v33, v39
	v_add_u32_e32 v33, 0x18600, v50
	ds_write_b32 v33, v28
	ds_write_b32 v24, v30
	v_lshl_add_u32 v24, v27, 2, v66
	v_ashrrev_i32_e32 v33, 31, v32
	ds_write_b32 v25, v29
	ds_write_b32 v24, v31
	v_lshl_add_u64 v[24:25], v[32:33], 1, s[30:31]
	v_lshl_add_u32 v27, v53, 2, s33
	v_and_b32_e32 v101, 7, v53
	s_add_i32 s12, s72, s80
	v_lshl_add_u32 v101, v101, 3, s12
	s_add_i32 s12, s72, s73
	s_add_i32 s12, s12, -1
	v_min_u32_e32 v101, s12, v101
	v_lshlrev_b32_e32 v101, 5, v101
	s_mov_b32 s12, s57
	s_mov_b32 s13, s60
	global_load_dword v100, v101, s[12:13]
	s_waitcnt lgkmcnt(0)
	s_barrier
	s_waitcnt vmcnt(0)
	s_branch .LBB0_1396

.LBB0_1396:
	v_add_u32_e32 v28, s0, v27
	ds_read_b32 v29, v28 offset:33280
	s_cmp_ge_u32 s1, s73
	s_waitcnt lgkmcnt(0)
	v_add_f32_dpp v30, v29, v29 quad_perm:[1,0,3,2] row_mask:0xf bank_mask:0xf bound_ctrl:1
	s_nop 1
	v_add_f32_dpp v30, v30, v30 quad_perm:[2,3,0,1] row_mask:0xf bank_mask:0xf bound_ctrl:1
	s_nop 1
	v_add_f32_dpp v30, v30, v30 row_half_mirror row_mask:0xf bank_mask:0xf bound_ctrl:1
	s_nop 1
	v_add_f32_dpp v30, v30, v30 row_mirror row_mask:0xf bank_mask:0xf bound_ctrl:1
	s_nop 0
	v_readlane_b32 s7, v30, 16
	v_readlane_b32 s6, v30, 0
	v_readlane_b32 s8, v30, 32
	v_readlane_b32 s9, v30, 48
	v_mov_b32_e32 v30, s7
	v_add_f32_e32 v30, s6, v30
	v_add_f32_e32 v30, s8, v30
	v_add_f32_e32 v30, s9, v30
	v_fmac_f32_e32 v29, 0xbc800000, v30
	v_mul_f32_e32 v30, v29, v29
	s_nop 1
	v_mov_b32_dpp v30, v30 quad_perm:[1,0,3,2] row_mask:0xf bank_mask:0xf bound_ctrl:1
	v_fmac_f32_e32 v30, v29, v29
	s_nop 1
	v_add_f32_dpp v30, v30, v30 quad_perm:[2,3,0,1] row_mask:0xf bank_mask:0xf bound_ctrl:1
	s_nop 1
	v_add_f32_dpp v30, v30, v30 row_half_mirror row_mask:0xf bank_mask:0xf bound_ctrl:1
	s_nop 1
	v_add_f32_dpp v30, v30, v30 row_mirror row_mask:0xf bank_mask:0xf bound_ctrl:1
	s_nop 0
	v_readlane_b32 s6, v30, 0
	v_readlane_b32 s9, v30, 16
	v_readlane_b32 s7, v30, 32
	v_readlane_b32 s8, v30, 48
	s_cbranch_scc1 .LBB0_1398
	s_add_i32 s10, s72, s1
	s_ashr_i32 s11, s10, 31
	s_sub_i32 s12, s1, s80
	s_lshr_b32 s12, s12, 3
	v_readlane_b32 s12, v100, s12
	s_nop 1
	v_mov_b32_e32 v53, s12
	v_mov_b32_e32 v30, s9
	v_add_f32_e32 v30, s6, v30
	v_add_f32_e32 v30, s7, v30
	v_add_f32_e32 v30, s8, v30
	v_fmamk_f32 v30, v30, 0x3c800000, v51
	v_mul_f32_e32 v33, 0x4b800000, v30
	v_cmp_gt_f32_e32 vcc, s70, v30
	v_add_u32_e32 v31, 0x18600, v28
	v_add_u32_e32 v32, 0x14500, v28
	v_cndmask_b32_e32 v30, v30, v33, vcc
	v_rsq_f32_e32 v30, v30
	ds_read_b32 v33, v31
	ds_read_b32 v31, v32
	s_lshl_b64 s[6:7], s[10:11], 11
	v_mul_f32_e32 v32, 0x45800000, v30
	v_cndmask_b32_e32 v30, v30, v32, vcc
	v_mul_f32_e32 v30, v29, v30
	s_waitcnt lgkmcnt(0)
	v_pk_mul_f32 v[30:31], v[52:53], v[30:31]
	s_nop 0
	v_add_f32_e32 v29, v35, v30
	v_add_f32_e32 v29, v29, v31
	v_mul_f32_e32 v29, v33, v29
	v_cvt_pk_bf16_f32 v29, v29, s0
	v_lshl_add_u64 v[30:31], v[24:25], 0, s[6:7]
	global_store_short v[30:31], v29, off
.LBB0_1398:
	ds_read_b32 v29, v28 offset:35360
	s_add_i32 s8, s1, 8
	s_cmp_ge_u32 s8, s73
	s_waitcnt lgkmcnt(0)
	v_add_f32_dpp v30, v29, v29 quad_perm:[1,0,3,2] row_mask:0xf bank_mask:0xf bound_ctrl:1
	s_nop 1
	v_add_f32_dpp v30, v30, v30 quad_perm:[2,3,0,1] row_mask:0xf bank_mask:0xf bound_ctrl:1
	s_nop 1
	v_add_f32_dpp v30, v30, v30 row_half_mirror row_mask:0xf bank_mask:0xf bound_ctrl:1
	s_nop 1
	v_add_f32_dpp v30, v30, v30 row_mirror row_mask:0xf bank_mask:0xf bound_ctrl:1
	s_nop 0
	v_readlane_b32 s7, v30, 16
	v_readlane_b32 s6, v30, 0
	v_readlane_b32 s9, v30, 32
	v_readlane_b32 s10, v30, 48
	v_mov_b32_e32 v30, s7
	v_add_f32_e32 v30, s6, v30
	v_add_f32_e32 v30, s9, v30
	v_add_f32_e32 v30, s10, v30
	v_fmac_f32_e32 v29, 0xbc800000, v30
	v_mul_f32_e32 v30, v29, v29
	s_nop 1
	v_mov_b32_dpp v30, v30 quad_perm:[1,0,3,2] row_mask:0xf bank_mask:0xf bound_ctrl:1
	v_fmac_f32_e32 v30, v29, v29
	s_nop 1
	v_add_f32_dpp v30, v30, v30 quad_perm:[2,3,0,1] row_mask:0xf bank_mask:0xf bound_ctrl:1
	s_nop 1
	v_add_f32_dpp v30, v30, v30 row_half_mirror row_mask:0xf bank_mask:0xf bound_ctrl:1
	s_nop 1
	v_add_f32_dpp v30, v30, v30 row_mirror row_mask:0xf bank_mask:0xf bound_ctrl:1
	s_nop 0
	v_readlane_b32 s6, v30, 0
	v_readlane_b32 s9, v30, 16
	v_readlane_b32 s7, v30, 32
	v_readlane_b32 s8, v30, 48
	s_cbranch_scc1 .LBB0_1395
	s_add_i32 s10, s72, s1
	s_add_i32 s10, s10, 8
	s_ashr_i32 s11, s10, 31
	s_sub_i32 s12, s1, s80
	s_lshr_b32 s12, s12, 3
	s_add_i32 s12, s12, 1
	v_readlane_b32 s12, v100, s12
	s_nop 1
	v_mov_b32_e32 v53, s12
	v_mov_b32_e32 v30, s9
	v_add_f32_e32 v30, s6, v30
	v_add_f32_e32 v30, s7, v30
	v_add_f32_e32 v30, s8, v30
	v_fmamk_f32 v30, v30, 0x3c800000, v51
	v_mul_f32_e32 v32, 0x4b800000, v30
	v_cmp_gt_f32_e32 vcc, s70, v30
	v_add_u32_e32 v31, 0x18e20, v28
	v_add_u32_e32 v28, 0x14d20, v28
	v_cndmask_b32_e32 v30, v30, v32, vcc
	v_rsq_f32_e32 v30, v30
	ds_read_b32 v32, v31
	ds_read_b32 v31, v28
	s_lshl_b64 s[6:7], s[10:11], 11
	v_mul_f32_e32 v28, 0x45800000, v30
	v_cndmask_b32_e32 v28, v30, v28, vcc
	v_mul_f32_e32 v30, v29, v28
	s_waitcnt lgkmcnt(0)
	v_pk_mul_f32 v[28:29], v[52:53], v[30:31]
	s_nop 0
	v_add_f32_e32 v28, v35, v28
	v_add_f32_e32 v28, v28, v29
	v_mul_f32_e32 v28, v32, v28
	v_cvt_pk_bf16_f32 v30, v28, s0
	v_lshl_add_u64 v[28:29], v[24:25], 0, s[6:7]
	global_store_short v[28:29], v30, off
	s_branch .LBB0_1395

.LBB0_1467:
	s_and_b64 vcc, exec, s[2:3]
	s_mov_b32 s18, s10
	s_mov_b32 s20, s12
	s_mov_b64 s[24:25], s[16:17]
	s_mov_b64 s[22:23], s[14:15]
	s_cbranch_vccnz .LBB0_1508

.LBB0_1475:
	ds_read_b128 v[146:149], v155
	ds_read_b128 v[160:163], v155 offset:1024
	ds_read_b128 v[164:167], v155 offset:2048
	ds_read_b128 v[168:171], v155 offset:3072
	s_add_u32 s24, s22, 0xfffc0080
	s_addc_u32 s25, s23, -1
	s_cmp_eq_u32 s63, 12
	s_cselect_b32 s27, s0, s25
	s_cselect_b32 s26, s1, s24
	s_cselect_b32 s25, s11, s62
	s_cselect_b32 s24, s13, s61
	s_mov_b32 m0, s54
	v_lshl_add_u64 v[150:151], s[22:23], 0, v[138:139]
	ds_read_b128 v[172:175], v153
	ds_read_b128 v[176:179], v153 offset:1024
	ds_read_b128 v[180:183], v153 offset:2048
	ds_read_b128 v[184:187], v153 offset:3072
	ds_read_b128 v[188:191], v153 offset:4096
	ds_read_b128 v[192:195], v153 offset:5120
	ds_read_b128 v[196:199], v153 offset:6144
	ds_read_b128 v[200:203], v153 offset:7168
	global_load_lds_dwordx4 v[150:151], off
	v_lshl_add_u64 v[150:151], s[22:23], 0, v[140:141]
	s_mov_b32 m0, s55
	s_nop 0
	global_load_lds_dwordx4 v[150:151], off
	s_waitcnt lgkmcnt(8)
	s_barrier
	s_waitcnt lgkmcnt(0)
	s_setprio 1
	s_waitcnt lgkmcnt(0)
	v_mfma_f32_16x16x32_bf16 v[124:127], v[146:149], v[172:175], v[124:127]
	v_mfma_f32_16x16x32_bf16 v[120:123], v[164:167], v[172:175], v[120:123]
	v_mfma_f32_16x16x32_bf16 v[108:111], v[146:149], v[180:183], v[108:111]
	v_mfma_f32_16x16x32_bf16 v[104:107], v[164:167], v[180:183], v[104:107]
	v_mfma_f32_16x16x32_bf16 v[92:95], v[146:149], v[188:191], v[92:95]
	v_mfma_f32_16x16x32_bf16 v[88:91], v[164:167], v[188:191], v[88:91]
	v_mfma_f32_16x16x32_bf16 v[76:79], v[146:149], v[196:199], v[76:79]
	v_mfma_f32_16x16x32_bf16 v[72:75], v[164:167], v[196:199], v[72:75]
	v_mfma_f32_16x16x32_bf16 v[124:127], v[160:163], v[176:179], v[124:127]
	v_mfma_f32_16x16x32_bf16 v[120:123], v[168:171], v[176:179], v[120:123]
	v_mfma_f32_16x16x32_bf16 v[108:111], v[160:163], v[184:187], v[108:111]
	v_mfma_f32_16x16x32_bf16 v[104:107], v[168:171], v[184:187], v[104:107]
	v_mfma_f32_16x16x32_bf16 v[92:95], v[160:163], v[192:195], v[92:95]
	v_mfma_f32_16x16x32_bf16 v[88:91], v[168:171], v[192:195], v[88:91]
	v_mfma_f32_16x16x32_bf16 v[76:79], v[160:163], v[200:203], v[76:79]
	v_mfma_f32_16x16x32_bf16 v[72:75], v[168:171], v[200:203], v[72:75]
	s_setprio 0
	s_barrier
	s_mov_b32 m0, s19
	v_lshl_add_u64 v[150:151], s[24:25], 0, v[130:131]
	ds_read_b128 v[204:207], v156
	ds_read_b128 v[208:211], v156 offset:1024
	ds_read_b128 v[212:215], v156 offset:2048
	ds_read_b128 v[216:219], v156 offset:3072
	global_load_lds_dwordx4 v[150:151], off
	v_lshl_add_u64 v[220:221], s[24:25], 0, v[134:135]
	s_mov_b32 m0, s21
	s_nop 0
	global_load_lds_dwordx4 v[220:221], off
	s_barrier
	s_waitcnt lgkmcnt(0)
	s_setprio 1
	s_waitcnt lgkmcnt(0)
	v_mfma_f32_16x16x32_bf16 v[116:119], v[204:207], v[172:175], v[116:119]
	v_mfma_f32_16x16x32_bf16 v[112:115], v[212:215], v[172:175], v[112:115]
	v_mfma_f32_16x16x32_bf16 v[100:103], v[204:207], v[180:183], v[100:103]
	v_mfma_f32_16x16x32_bf16 v[96:99], v[212:215], v[180:183], v[96:99]
	v_mfma_f32_16x16x32_bf16 v[84:87], v[204:207], v[188:191], v[84:87]
	v_mfma_f32_16x16x32_bf16 v[80:83], v[212:215], v[188:191], v[80:83]
	v_mfma_f32_16x16x32_bf16 v[68:71], v[204:207], v[196:199], v[68:71]
	v_mfma_f32_16x16x32_bf16 v[64:67], v[212:215], v[196:199], v[64:67]
	v_mfma_f32_16x16x32_bf16 v[116:119], v[208:211], v[176:179], v[116:119]
	v_mfma_f32_16x16x32_bf16 v[112:115], v[216:219], v[176:179], v[112:115]
	v_mfma_f32_16x16x32_bf16 v[100:103], v[208:211], v[184:187], v[100:103]
	v_mfma_f32_16x16x32_bf16 v[96:99], v[216:219], v[184:187], v[96:99]
	v_mfma_f32_16x16x32_bf16 v[84:87], v[208:211], v[192:195], v[84:87]
	v_mfma_f32_16x16x32_bf16 v[80:83], v[216:219], v[192:195], v[80:83]
	v_mfma_f32_16x16x32_bf16 v[68:71], v[208:211], v[200:203], v[68:71]
	v_mfma_f32_16x16x32_bf16 v[64:67], v[216:219], v[200:203], v[64:67]
	s_setprio 0
	s_mov_b32 m0, s35
	v_lshl_add_u64 v[222:223], s[26:27], 0, v[128:129]
	s_barrier
	ds_read_b128 v[172:175], v153 offset:16384
	ds_read_b128 v[176:179], v153 offset:17408
	ds_read_b128 v[180:183], v153 offset:18432
	ds_read_b128 v[184:187], v153 offset:19456
	ds_read_b128 v[188:191], v153 offset:20480
	ds_read_b128 v[192:195], v153 offset:21504
	ds_read_b128 v[196:199], v153 offset:22528
	ds_read_b128 v[200:203], v153 offset:23552
	global_load_lds_dwordx4 v[222:223], off
	v_lshl_add_u64 v[224:225], s[26:27], 0, v[132:133]
	s_mov_b32 m0, s40
	s_nop 0
	global_load_lds_dwordx4 v[224:225], off
	s_barrier
	s_waitcnt lgkmcnt(0)
	s_setprio 1
	s_waitcnt lgkmcnt(0)
	v_mfma_f32_16x16x32_bf16 v[60:63], v[146:149], v[172:175], v[60:63]
	v_mfma_f32_16x16x32_bf16 v[56:59], v[164:167], v[172:175], v[56:59]
	v_mfma_f32_16x16x32_bf16 v[44:47], v[146:149], v[180:183], v[44:47]
	v_mfma_f32_16x16x32_bf16 v[40:43], v[164:167], v[180:183], v[40:43]
	v_mfma_f32_16x16x32_bf16 v[28:31], v[146:149], v[188:191], v[28:31]
	v_mfma_f32_16x16x32_bf16 v[24:27], v[164:167], v[188:191], v[24:27]
	v_mfma_f32_16x16x32_bf16 v[12:15], v[146:149], v[196:199], v[12:15]
	v_mfma_f32_16x16x32_bf16 v[8:11], v[164:167], v[196:199], v[8:11]
	v_mfma_f32_16x16x32_bf16 v[60:63], v[160:163], v[176:179], v[60:63]
	v_mfma_f32_16x16x32_bf16 v[56:59], v[168:171], v[176:179], v[56:59]
	v_mfma_f32_16x16x32_bf16 v[44:47], v[160:163], v[184:187], v[44:47]
	v_mfma_f32_16x16x32_bf16 v[40:43], v[168:171], v[184:187], v[40:43]
	v_mfma_f32_16x16x32_bf16 v[28:31], v[160:163], v[192:195], v[28:31]
	v_mfma_f32_16x16x32_bf16 v[24:27], v[168:171], v[192:195], v[24:27]
	v_mfma_f32_16x16x32_bf16 v[12:15], v[160:163], v[200:203], v[12:15]
	v_mfma_f32_16x16x32_bf16 v[8:11], v[168:171], v[200:203], v[8:11]
	s_setprio 0
	s_barrier
	s_add_u32 s64, s24, 0x40000
	s_addc_u32 s65, s25, 0
	s_mov_b32 m0, s41
	v_lshl_add_u64 v[146:147], s[64:65], 0, v[130:131]
	global_load_lds_dwordx4 v[146:147], off
	v_lshl_add_u64 v[146:147], s[64:65], 0, v[134:135]
	s_mov_b32 m0, s42
	s_nop 0
	global_load_lds_dwordx4 v[146:147], off
	s_waitcnt vmcnt(6)
	s_barrier
	s_setprio 1
	v_mfma_f32_16x16x32_bf16 v[52:55], v[204:207], v[172:175], v[52:55]
	v_mfma_f32_16x16x32_bf16 v[48:51], v[212:215], v[172:175], v[48:51]
	v_mfma_f32_16x16x32_bf16 v[36:39], v[204:207], v[180:183], v[36:39]
	v_mfma_f32_16x16x32_bf16 v[32:35], v[212:215], v[180:183], v[32:35]
	v_mfma_f32_16x16x32_bf16 v[20:23], v[204:207], v[188:191], v[20:23]
	v_mfma_f32_16x16x32_bf16 v[16:19], v[212:215], v[188:191], v[16:19]
	v_mfma_f32_16x16x32_bf16 v[4:7], v[204:207], v[196:199], v[4:7]
	v_mfma_f32_16x16x32_bf16 v[0:3], v[212:215], v[196:199], v[0:3]
	v_mfma_f32_16x16x32_bf16 v[52:55], v[208:211], v[176:179], v[52:55]
	v_mfma_f32_16x16x32_bf16 v[48:51], v[216:219], v[176:179], v[48:51]
	v_mfma_f32_16x16x32_bf16 v[36:39], v[208:211], v[184:187], v[36:39]
	v_mfma_f32_16x16x32_bf16 v[32:35], v[216:219], v[184:187], v[32:35]
	v_mfma_f32_16x16x32_bf16 v[20:23], v[208:211], v[192:195], v[20:23]
	v_mfma_f32_16x16x32_bf16 v[16:19], v[216:219], v[192:195], v[16:19]
	v_mfma_f32_16x16x32_bf16 v[4:7], v[208:211], v[200:203], v[4:7]
	v_mfma_f32_16x16x32_bf16 v[0:3], v[216:219], v[200:203], v[0:3]
	s_setprio 0
	s_barrier
	ds_read_b128 v[146:149], v157
	ds_read_b128 v[160:163], v157 offset:1024
	ds_read_b128 v[164:167], v157 offset:2048
	ds_read_b128 v[168:171], v157 offset:3072
	s_add_u32 s26, s26, 0x40000
	s_addc_u32 s27, s27, 0
	s_mov_b32 m0, s43
	v_lshl_add_u64 v[204:205], s[26:27], 0, v[128:129]
	ds_read_b128 v[172:175], v153 offset:32768
	ds_read_b128 v[176:179], v153 offset:33792
	ds_read_b128 v[180:183], v153 offset:34816
	ds_read_b128 v[184:187], v153 offset:35840
	ds_read_b128 v[188:191], v153 offset:36864
	ds_read_b128 v[192:195], v153 offset:37888
	ds_read_b128 v[196:199], v153 offset:38912
	ds_read_b128 v[200:203], v153 offset:39936
	global_load_lds_dwordx4 v[204:205], off
	v_lshl_add_u64 v[204:205], s[26:27], 0, v[132:133]
	s_mov_b32 m0, s44
	s_nop 0
	global_load_lds_dwordx4 v[204:205], off
	s_waitcnt lgkmcnt(8)
	s_barrier
	s_waitcnt lgkmcnt(0)
	s_setprio 1
	s_waitcnt lgkmcnt(0)
	v_mfma_f32_16x16x32_bf16 v[124:127], v[146:149], v[172:175], v[124:127]
	v_mfma_f32_16x16x32_bf16 v[120:123], v[164:167], v[172:175], v[120:123]
	v_mfma_f32_16x16x32_bf16 v[108:111], v[146:149], v[180:183], v[108:111]
	v_mfma_f32_16x16x32_bf16 v[104:107], v[164:167], v[180:183], v[104:107]
	v_mfma_f32_16x16x32_bf16 v[92:95], v[146:149], v[188:191], v[92:95]
	v_mfma_f32_16x16x32_bf16 v[88:91], v[164:167], v[188:191], v[88:91]
	v_mfma_f32_16x16x32_bf16 v[76:79], v[146:149], v[196:199], v[76:79]
	v_mfma_f32_16x16x32_bf16 v[72:75], v[164:167], v[196:199], v[72:75]
	v_mfma_f32_16x16x32_bf16 v[124:127], v[160:163], v[176:179], v[124:127]
	v_mfma_f32_16x16x32_bf16 v[120:123], v[168:171], v[176:179], v[120:123]
	v_mfma_f32_16x16x32_bf16 v[108:111], v[160:163], v[184:187], v[108:111]
	v_mfma_f32_16x16x32_bf16 v[104:107], v[168:171], v[184:187], v[104:107]
	v_mfma_f32_16x16x32_bf16 v[92:95], v[160:163], v[192:195], v[92:95]
	v_mfma_f32_16x16x32_bf16 v[88:91], v[168:171], v[192:195], v[88:91]
	v_mfma_f32_16x16x32_bf16 v[76:79], v[160:163], v[200:203], v[76:79]
	v_mfma_f32_16x16x32_bf16 v[72:75], v[168:171], v[200:203], v[72:75]
	s_setprio 0
	s_barrier
	s_mov_b32 m0, s45
	v_lshl_add_u64 v[150:151], v[150:151], 0, s[8:9]
	ds_read_b128 v[204:207], v158
	ds_read_b128 v[208:211], v158 offset:1024
	ds_read_b128 v[212:215], v158 offset:2048
	ds_read_b128 v[216:219], v158 offset:3072
	global_load_lds_dwordx4 v[150:151], off
	v_lshl_add_u64 v[150:151], v[220:221], 0, s[8:9]
	s_mov_b32 m0, s46
	s_nop 0
	global_load_lds_dwordx4 v[150:151], off
	s_barrier
	s_waitcnt lgkmcnt(0)
	s_setprio 1
	s_waitcnt lgkmcnt(0)
	v_mfma_f32_16x16x32_bf16 v[116:119], v[204:207], v[172:175], v[116:119]
	v_mfma_f32_16x16x32_bf16 v[112:115], v[212:215], v[172:175], v[112:115]
	v_mfma_f32_16x16x32_bf16 v[100:103], v[204:207], v[180:183], v[100:103]
	v_mfma_f32_16x16x32_bf16 v[96:99], v[212:215], v[180:183], v[96:99]
	v_mfma_f32_16x16x32_bf16 v[84:87], v[204:207], v[188:191], v[84:87]
	v_mfma_f32_16x16x32_bf16 v[80:83], v[212:215], v[188:191], v[80:83]
	v_mfma_f32_16x16x32_bf16 v[68:71], v[204:207], v[196:199], v[68:71]
	v_mfma_f32_16x16x32_bf16 v[64:67], v[212:215], v[196:199], v[64:67]
	v_mfma_f32_16x16x32_bf16 v[116:119], v[208:211], v[176:179], v[116:119]
	v_mfma_f32_16x16x32_bf16 v[112:115], v[216:219], v[176:179], v[112:115]
	v_mfma_f32_16x16x32_bf16 v[100:103], v[208:211], v[184:187], v[100:103]
	v_mfma_f32_16x16x32_bf16 v[96:99], v[216:219], v[184:187], v[96:99]
	v_mfma_f32_16x16x32_bf16 v[84:87], v[208:211], v[192:195], v[84:87]
	v_mfma_f32_16x16x32_bf16 v[80:83], v[216:219], v[192:195], v[80:83]
	v_mfma_f32_16x16x32_bf16 v[68:71], v[208:211], v[200:203], v[68:71]
	v_mfma_f32_16x16x32_bf16 v[64:67], v[216:219], v[200:203], v[64:67]
	s_setprio 0
	s_mov_b32 m0, s47
	v_lshl_add_u64 v[150:151], v[222:223], 0, s[8:9]
	s_barrier
	ds_read_b128 v[172:175], v153 offset:49152
	ds_read_b128 v[176:179], v153 offset:50176
	ds_read_b128 v[180:183], v153 offset:51200
	ds_read_b128 v[184:187], v153 offset:52224
	ds_read_b128 v[188:191], v153 offset:53248
	ds_read_b128 v[192:195], v153 offset:54272
	ds_read_b128 v[196:199], v153 offset:55296
	ds_read_b128 v[200:203], v153 offset:56320
	global_load_lds_dwordx4 v[150:151], off
	v_lshl_add_u64 v[150:151], v[224:225], 0, s[8:9]
	s_mov_b32 m0, s48
	s_nop 0
	global_load_lds_dwordx4 v[150:151], off
	s_barrier
	s_waitcnt lgkmcnt(0)
	s_setprio 1
	s_waitcnt lgkmcnt(0)
	v_mfma_f32_16x16x32_bf16 v[60:63], v[146:149], v[172:175], v[60:63]
	v_mfma_f32_16x16x32_bf16 v[56:59], v[164:167], v[172:175], v[56:59]
	v_mfma_f32_16x16x32_bf16 v[44:47], v[146:149], v[180:183], v[44:47]
	v_mfma_f32_16x16x32_bf16 v[40:43], v[164:167], v[180:183], v[40:43]
	v_mfma_f32_16x16x32_bf16 v[28:31], v[146:149], v[188:191], v[28:31]
	v_mfma_f32_16x16x32_bf16 v[24:27], v[164:167], v[188:191], v[24:27]
	v_mfma_f32_16x16x32_bf16 v[12:15], v[146:149], v[196:199], v[12:15]
	v_mfma_f32_16x16x32_bf16 v[8:11], v[164:167], v[196:199], v[8:11]
	v_mfma_f32_16x16x32_bf16 v[60:63], v[160:163], v[176:179], v[60:63]
	v_mfma_f32_16x16x32_bf16 v[56:59], v[168:171], v[176:179], v[56:59]
	v_mfma_f32_16x16x32_bf16 v[44:47], v[160:163], v[184:187], v[44:47]
	v_mfma_f32_16x16x32_bf16 v[40:43], v[168:171], v[184:187], v[40:43]
	v_mfma_f32_16x16x32_bf16 v[28:31], v[160:163], v[192:195], v[28:31]
	v_mfma_f32_16x16x32_bf16 v[24:27], v[168:171], v[192:195], v[24:27]
	v_mfma_f32_16x16x32_bf16 v[12:15], v[160:163], v[200:203], v[12:15]
	v_mfma_f32_16x16x32_bf16 v[8:11], v[168:171], v[200:203], v[8:11]
	s_setprio 0
	s_barrier
	s_add_u32 s24, s24, 0x40080
	s_addc_u32 s25, s25, 0
	s_mov_b32 m0, s49
	v_lshl_add_u64 v[146:147], s[24:25], 0, v[130:131]
	global_load_lds_dwordx4 v[146:147], off
	v_lshl_add_u64 v[146:147], s[24:25], 0, v[134:135]
	s_mov_b32 m0, s50
	s_nop 0
	global_load_lds_dwordx4 v[146:147], off
	s_waitcnt vmcnt(6)
	s_barrier
	s_setprio 1
	v_mfma_f32_16x16x32_bf16 v[52:55], v[204:207], v[172:175], v[52:55]
	v_mfma_f32_16x16x32_bf16 v[48:51], v[212:215], v[172:175], v[48:51]
	v_mfma_f32_16x16x32_bf16 v[36:39], v[204:207], v[180:183], v[36:39]
	v_mfma_f32_16x16x32_bf16 v[32:35], v[212:215], v[180:183], v[32:35]
	v_mfma_f32_16x16x32_bf16 v[20:23], v[204:207], v[188:191], v[20:23]
	v_mfma_f32_16x16x32_bf16 v[16:19], v[212:215], v[188:191], v[16:19]
	v_mfma_f32_16x16x32_bf16 v[4:7], v[204:207], v[196:199], v[4:7]
	v_mfma_f32_16x16x32_bf16 v[0:3], v[212:215], v[196:199], v[0:3]
	v_mfma_f32_16x16x32_bf16 v[52:55], v[208:211], v[176:179], v[52:55]
	v_mfma_f32_16x16x32_bf16 v[48:51], v[216:219], v[176:179], v[48:51]
	v_mfma_f32_16x16x32_bf16 v[36:39], v[208:211], v[184:187], v[36:39]
	v_mfma_f32_16x16x32_bf16 v[32:35], v[216:219], v[184:187], v[32:35]
	v_mfma_f32_16x16x32_bf16 v[20:23], v[208:211], v[192:195], v[20:23]
	v_mfma_f32_16x16x32_bf16 v[16:19], v[216:219], v[192:195], v[16:19]
	v_mfma_f32_16x16x32_bf16 v[4:7], v[208:211], v[200:203], v[4:7]
	v_mfma_f32_16x16x32_bf16 v[0:3], v[216:219], v[200:203], v[0:3]
	s_setprio 0
	s_add_i32 s63, s63, 2
	s_add_u32 s22, s22, 0x100
	s_addc_u32 s23, s23, 0
	s_add_u32 s61, s61, 0x100
	s_addc_u32 s62, s62, 0
	s_cmp_gt_u32 s63, 13
	s_barrier
	s_cbranch_scc0 .LBB0_1475
	v_lshl_add_u32 v148, s20, 8, v152
	v_lshl_add_u32 v146, s18, 8, v154
	v_ashrrev_i32_e32 v147, 31, v146
	v_mov_b32_e32 v252, v148
	v_cmp_lt_i32_e32 vcc, s56, v252
	s_and_saveexec_b64 s[0:1], vcc
	s_xor_b64 s[0:1], exec, s[0:1]
	v_add_u32_e32 v136, 0xffff8000, v148
	v_lshlrev_b64 v[250:251], 12, v[136:137]
	v_lshl_add_u64 v[250:251], s[38:39], 0, v[250:251]
	v_mov_b32_e32 v253, v137
	s_andn2_saveexec_b64 s[0:1], s[0:1]
	v_ashrrev_i32_e32 v253, 31, v252
	v_lshlrev_b64 v[250:251], 12, v[252:253]
	v_lshl_add_u64 v[250:251], s[36:37], 0, v[250:251]
	s_or_b64 exec, exec, s[0:1]
	v_lshl_add_u64 v[250:251], v[146:147], 2, v[250:251]
	global_load_dwordx4 v[160:163], v[250:251], off
	global_load_dwordx4 v[164:167], v[250:251], off offset:16
	global_load_dwordx4 v[168:171], v[250:251], off offset:512
	global_load_dwordx4 v[172:175], v[250:251], off offset:528
	v_lshlrev_b64 v[242:243], 11, v[252:253]
	v_lshl_add_u64 v[242:243], s[6:7], 0, v[242:243]
	v_lshl_add_u64 v[242:243], v[146:147], 1, v[242:243]
	v_or_b32_e32 v252, 16, v148
	v_cmp_lt_i32_e32 vcc, s56, v252
	s_and_saveexec_b64 s[0:1], vcc
	s_xor_b64 s[0:1], exec, s[0:1]
	v_add_u32_e32 v136, 0xffff8010, v148
	v_lshlrev_b64 v[250:251], 12, v[136:137]
	v_lshl_add_u64 v[250:251], s[38:39], 0, v[250:251]
	v_mov_b32_e32 v253, v137
	s_andn2_saveexec_b64 s[0:1], s[0:1]
	v_ashrrev_i32_e32 v253, 31, v252
	v_lshlrev_b64 v[250:251], 12, v[252:253]
	v_lshl_add_u64 v[250:251], s[36:37], 0, v[250:251]
	s_or_b64 exec, exec, s[0:1]
	v_lshl_add_u64 v[250:251], v[146:147], 2, v[250:251]
	global_load_dwordx4 v[176:179], v[250:251], off
	global_load_dwordx4 v[180:183], v[250:251], off offset:16
	global_load_dwordx4 v[184:187], v[250:251], off offset:512
	global_load_dwordx4 v[188:191], v[250:251], off offset:528
	v_lshlrev_b64 v[244:245], 11, v[252:253]
	v_lshl_add_u64 v[244:245], s[6:7], 0, v[244:245]
	v_lshl_add_u64 v[244:245], v[146:147], 1, v[244:245]
	v_or_b32_e32 v252, 32, v148
	v_cmp_lt_i32_e32 vcc, s56, v252
	s_and_saveexec_b64 s[0:1], vcc
	s_xor_b64 s[0:1], exec, s[0:1]
	v_add_u32_e32 v136, 0xffff8020, v148
	v_lshlrev_b64 v[250:251], 12, v[136:137]
	v_lshl_add_u64 v[250:251], s[38:39], 0, v[250:251]
	v_mov_b32_e32 v253, v137
	s_andn2_saveexec_b64 s[0:1], s[0:1]
	v_ashrrev_i32_e32 v253, 31, v252
	v_lshlrev_b64 v[250:251], 12, v[252:253]
	v_lshl_add_u64 v[250:251], s[36:37], 0, v[250:251]
	s_or_b64 exec, exec, s[0:1]
	v_lshl_add_u64 v[250:251], v[146:147], 2, v[250:251]
	global_load_dwordx4 v[192:195], v[250:251], off
	global_load_dwordx4 v[196:199], v[250:251], off offset:16
	global_load_dwordx4 v[200:203], v[250:251], off offset:512
	global_load_dwordx4 v[204:207], v[250:251], off offset:528
	v_lshlrev_b64 v[246:247], 11, v[252:253]
	v_lshl_add_u64 v[246:247], s[6:7], 0, v[246:247]
	v_lshl_add_u64 v[246:247], v[146:147], 1, v[246:247]
	v_or_b32_e32 v252, 48, v148
	v_cmp_lt_i32_e32 vcc, s56, v252
	s_and_saveexec_b64 s[0:1], vcc
	s_xor_b64 s[0:1], exec, s[0:1]
	v_add_u32_e32 v136, 0xffff8030, v148
	v_lshlrev_b64 v[250:251], 12, v[136:137]
	v_lshl_add_u64 v[250:251], s[38:39], 0, v[250:251]
	v_mov_b32_e32 v253, v137
	s_andn2_saveexec_b64 s[0:1], s[0:1]
	v_ashrrev_i32_e32 v253, 31, v252
	v_lshlrev_b64 v[250:251], 12, v[252:253]
	v_lshl_add_u64 v[250:251], s[36:37], 0, v[250:251]
	s_or_b64 exec, exec, s[0:1]
	v_lshl_add_u64 v[250:251], v[146:147], 2, v[250:251]
	global_load_dwordx4 v[226:229], v[250:251], off
	global_load_dwordx4 v[230:233], v[250:251], off offset:16
	global_load_dwordx4 v[234:237], v[250:251], off offset:512
	global_load_dwordx4 v[238:241], v[250:251], off offset:528
	v_lshlrev_b64 v[248:249], 11, v[252:253]
	v_lshl_add_u64 v[248:249], s[6:7], 0, v[248:249]
	v_lshl_add_u64 v[248:249], v[146:147], 1, v[248:249]
	s_waitcnt vmcnt(12)
	v_pk_add_f32 v[124:125], v[124:125], v[160:161]
	v_pk_add_f32 v[126:127], v[126:127], v[162:163]
	v_pk_add_f32 v[120:121], v[120:121], v[164:165]
	v_pk_add_f32 v[122:123], v[122:123], v[166:167]
	v_cvt_pk_bf16_f32 v124, v124, v125
	v_cvt_pk_bf16_f32 v125, v126, v127
	v_cvt_pk_bf16_f32 v126, v120, v121
	v_cvt_pk_bf16_f32 v127, v122, v123
	global_store_dwordx4 v[242:243], v[124:127], off
	v_pk_add_f32 v[116:117], v[116:117], v[168:169]
	v_pk_add_f32 v[118:119], v[118:119], v[170:171]
	v_pk_add_f32 v[112:113], v[112:113], v[172:173]
	v_pk_add_f32 v[114:115], v[114:115], v[174:175]
	v_cvt_pk_bf16_f32 v116, v116, v117
	v_cvt_pk_bf16_f32 v117, v118, v119
	v_cvt_pk_bf16_f32 v118, v112, v113
	v_cvt_pk_bf16_f32 v119, v114, v115
	global_store_dwordx4 v[242:243], v[116:119], off offset:256
	v_add_u32_e32 v252, 0x80, v148
	v_cmp_lt_i32_e32 vcc, s56, v252
	s_and_saveexec_b64 s[0:1], vcc
	s_xor_b64 s[0:1], exec, s[0:1]
	v_add_u32_e32 v136, 0xffff8080, v148
	v_lshlrev_b64 v[250:251], 12, v[136:137]
	v_lshl_add_u64 v[250:251], s[38:39], 0, v[250:251]
	v_mov_b32_e32 v253, v137
	s_andn2_saveexec_b64 s[0:1], s[0:1]
	v_ashrrev_i32_e32 v253, 31, v252
	v_lshlrev_b64 v[250:251], 12, v[252:253]
	v_lshl_add_u64 v[250:251], s[36:37], 0, v[250:251]
	s_or_b64 exec, exec, s[0:1]
	v_lshl_add_u64 v[250:251], v[146:147], 2, v[250:251]
	global_load_dwordx4 v[160:163], v[250:251], off
	global_load_dwordx4 v[164:167], v[250:251], off offset:16
	global_load_dwordx4 v[168:171], v[250:251], off offset:512
	global_load_dwordx4 v[172:175], v[250:251], off offset:528
	v_lshlrev_b64 v[242:243], 11, v[252:253]
	v_lshl_add_u64 v[242:243], s[6:7], 0, v[242:243]
	v_lshl_add_u64 v[242:243], v[146:147], 1, v[242:243]
	s_waitcnt vmcnt(14)
	v_pk_add_f32 v[108:109], v[108:109], v[176:177]
	v_pk_add_f32 v[110:111], v[110:111], v[178:179]
	v_pk_add_f32 v[104:105], v[104:105], v[180:181]
	v_pk_add_f32 v[106:107], v[106:107], v[182:183]
	v_cvt_pk_bf16_f32 v108, v108, v109
	v_cvt_pk_bf16_f32 v109, v110, v111
	v_cvt_pk_bf16_f32 v110, v104, v105
	v_cvt_pk_bf16_f32 v111, v106, v107
	global_store_dwordx4 v[244:245], v[108:111], off
	v_pk_add_f32 v[100:101], v[100:101], v[184:185]
	v_pk_add_f32 v[102:103], v[102:103], v[186:187]
	v_pk_add_f32 v[96:97], v[96:97], v[188:189]
	v_pk_add_f32 v[98:99], v[98:99], v[190:191]
	v_cvt_pk_bf16_f32 v100, v100, v101
	v_cvt_pk_bf16_f32 v101, v102, v103
	v_cvt_pk_bf16_f32 v102, v96, v97
	v_cvt_pk_bf16_f32 v103, v98, v99
	global_store_dwordx4 v[244:245], v[100:103], off offset:256
	v_add_u32_e32 v252, 0x90, v148
	v_cmp_lt_i32_e32 vcc, s56, v252
	s_and_saveexec_b64 s[0:1], vcc
	s_xor_b64 s[0:1], exec, s[0:1]
	v_add_u32_e32 v136, 0xffff8090, v148
	v_lshlrev_b64 v[250:251], 12, v[136:137]
	v_lshl_add_u64 v[250:251], s[38:39], 0, v[250:251]
	v_mov_b32_e32 v253, v137
	s_andn2_saveexec_b64 s[0:1], s[0:1]
	v_ashrrev_i32_e32 v253, 31, v252
	v_lshlrev_b64 v[250:251], 12, v[252:253]
	v_lshl_add_u64 v[250:251], s[36:37], 0, v[250:251]
	s_or_b64 exec, exec, s[0:1]
	v_lshl_add_u64 v[250:251], v[146:147], 2, v[250:251]
	global_load_dwordx4 v[176:179], v[250:251], off
	global_load_dwordx4 v[180:183], v[250:251], off offset:16
	global_load_dwordx4 v[184:187], v[250:251], off offset:512
	global_load_dwordx4 v[188:191], v[250:251], off offset:528
	v_lshlrev_b64 v[244:245], 11, v[252:253]
	v_lshl_add_u64 v[244:245], s[6:7], 0, v[244:245]
	v_lshl_add_u64 v[244:245], v[146:147], 1, v[244:245]
	s_waitcnt vmcnt(16)
	v_pk_add_f32 v[92:93], v[92:93], v[192:193]
	v_pk_add_f32 v[94:95], v[94:95], v[194:195]
	v_pk_add_f32 v[88:89], v[88:89], v[196:197]
	v_pk_add_f32 v[90:91], v[90:91], v[198:199]
	v_cvt_pk_bf16_f32 v92, v92, v93
	v_cvt_pk_bf16_f32 v93, v94, v95
	v_cvt_pk_bf16_f32 v94, v88, v89
	v_cvt_pk_bf16_f32 v95, v90, v91
	global_store_dwordx4 v[246:247], v[92:95], off
	v_pk_add_f32 v[84:85], v[84:85], v[200:201]
	v_pk_add_f32 v[86:87], v[86:87], v[202:203]
	v_pk_add_f32 v[80:81], v[80:81], v[204:205]
	v_pk_add_f32 v[82:83], v[82:83], v[206:207]
	v_cvt_pk_bf16_f32 v84, v84, v85
	v_cvt_pk_bf16_f32 v85, v86, v87
	v_cvt_pk_bf16_f32 v86, v80, v81
	v_cvt_pk_bf16_f32 v87, v82, v83
	global_store_dwordx4 v[246:247], v[84:87], off offset:256
	v_add_u32_e32 v252, 0xa0, v148
	v_cmp_lt_i32_e32 vcc, s56, v252
	s_and_saveexec_b64 s[0:1], vcc
	s_xor_b64 s[0:1], exec, s[0:1]
	v_add_u32_e32 v136, 0xffff80a0, v148
	v_lshlrev_b64 v[250:251], 12, v[136:137]
	v_lshl_add_u64 v[250:251], s[38:39], 0, v[250:251]
	v_mov_b32_e32 v253, v137
	s_andn2_saveexec_b64 s[0:1], s[0:1]
	v_ashrrev_i32_e32 v253, 31, v252
	v_lshlrev_b64 v[250:251], 12, v[252:253]
	v_lshl_add_u64 v[250:251], s[36:37], 0, v[250:251]
	s_or_b64 exec, exec, s[0:1]
	v_lshl_add_u64 v[250:251], v[146:147], 2, v[250:251]
	global_load_dwordx4 v[192:195], v[250:251], off
	global_load_dwordx4 v[196:199], v[250:251], off offset:16
	global_load_dwordx4 v[200:203], v[250:251], off offset:512
	global_load_dwordx4 v[204:207], v[250:251], off offset:528
	v_lshlrev_b64 v[246:247], 11, v[252:253]
	v_lshl_add_u64 v[246:247], s[6:7], 0, v[246:247]
	v_lshl_add_u64 v[246:247], v[146:147], 1, v[246:247]
	s_waitcnt vmcnt(18)
	v_pk_add_f32 v[76:77], v[76:77], v[226:227]
	v_pk_add_f32 v[78:79], v[78:79], v[228:229]
	v_pk_add_f32 v[72:73], v[72:73], v[230:231]
	v_pk_add_f32 v[74:75], v[74:75], v[232:233]
	v_cvt_pk_bf16_f32 v76, v76, v77
	v_cvt_pk_bf16_f32 v77, v78, v79
	v_cvt_pk_bf16_f32 v78, v72, v73
	v_cvt_pk_bf16_f32 v79, v74, v75
	global_store_dwordx4 v[248:249], v[76:79], off
	v_pk_add_f32 v[68:69], v[68:69], v[234:235]
	v_pk_add_f32 v[70:71], v[70:71], v[236:237]
	v_pk_add_f32 v[64:65], v[64:65], v[238:239]
	v_pk_add_f32 v[66:67], v[66:67], v[240:241]
	v_cvt_pk_bf16_f32 v68, v68, v69
	v_cvt_pk_bf16_f32 v69, v70, v71
	v_cvt_pk_bf16_f32 v70, v64, v65
	v_cvt_pk_bf16_f32 v71, v66, v67
	global_store_dwordx4 v[248:249], v[68:71], off offset:256
	v_add_u32_e32 v252, 0xb0, v148
	v_cmp_lt_i32_e32 vcc, s56, v252
	s_and_saveexec_b64 s[0:1], vcc
	s_xor_b64 s[0:1], exec, s[0:1]
	v_add_u32_e32 v136, 0xffff80b0, v148
	v_lshlrev_b64 v[250:251], 12, v[136:137]
	v_lshl_add_u64 v[250:251], s[38:39], 0, v[250:251]
	v_mov_b32_e32 v253, v137
	s_andn2_saveexec_b64 s[0:1], s[0:1]
	v_ashrrev_i32_e32 v253, 31, v252
	v_lshlrev_b64 v[250:251], 12, v[252:253]
	v_lshl_add_u64 v[250:251], s[36:37], 0, v[250:251]
	s_or_b64 exec, exec, s[0:1]
	v_lshl_add_u64 v[250:251], v[146:147], 2, v[250:251]
	global_load_dwordx4 v[226:229], v[250:251], off
	global_load_dwordx4 v[230:233], v[250:251], off offset:16
	global_load_dwordx4 v[234:237], v[250:251], off offset:512
	global_load_dwordx4 v[238:241], v[250:251], off offset:528
	v_lshlrev_b64 v[248:249], 11, v[252:253]
	v_lshl_add_u64 v[248:249], s[6:7], 0, v[248:249]
	v_lshl_add_u64 v[248:249], v[146:147], 1, v[248:249]
	s_waitcnt vmcnt(18)
	v_pk_add_f32 v[60:61], v[60:61], v[160:161]
	v_pk_add_f32 v[62:63], v[62:63], v[162:163]
	v_pk_add_f32 v[56:57], v[56:57], v[164:165]
	v_pk_add_f32 v[58:59], v[58:59], v[166:167]
	v_cvt_pk_bf16_f32 v60, v60, v61
	v_cvt_pk_bf16_f32 v61, v62, v63
	v_cvt_pk_bf16_f32 v62, v56, v57
	v_cvt_pk_bf16_f32 v63, v58, v59
	global_store_dwordx4 v[242:243], v[60:63], off
	v_pk_add_f32 v[52:53], v[52:53], v[168:169]
	v_pk_add_f32 v[54:55], v[54:55], v[170:171]
	v_pk_add_f32 v[48:49], v[48:49], v[172:173]
	v_pk_add_f32 v[50:51], v[50:51], v[174:175]
	v_cvt_pk_bf16_f32 v52, v52, v53
	v_cvt_pk_bf16_f32 v53, v54, v55
	v_cvt_pk_bf16_f32 v54, v48, v49
	v_cvt_pk_bf16_f32 v55, v50, v51
	global_store_dwordx4 v[242:243], v[52:55], off offset:256
	s_waitcnt vmcnt(14)
	v_pk_add_f32 v[44:45], v[44:45], v[176:177]
	v_pk_add_f32 v[46:47], v[46:47], v[178:179]
	v_pk_add_f32 v[40:41], v[40:41], v[180:181]
	v_pk_add_f32 v[42:43], v[42:43], v[182:183]
	v_cvt_pk_bf16_f32 v44, v44, v45
	v_cvt_pk_bf16_f32 v45, v46, v47
	v_cvt_pk_bf16_f32 v46, v40, v41
	v_cvt_pk_bf16_f32 v47, v42, v43
	global_store_dwordx4 v[244:245], v[44:47], off
	v_pk_add_f32 v[36:37], v[36:37], v[184:185]
	v_pk_add_f32 v[38:39], v[38:39], v[186:187]
	v_pk_add_f32 v[32:33], v[32:33], v[188:189]
	v_pk_add_f32 v[34:35], v[34:35], v[190:191]
	v_cvt_pk_bf16_f32 v36, v36, v37
	v_cvt_pk_bf16_f32 v37, v38, v39
	v_cvt_pk_bf16_f32 v38, v32, v33
	v_cvt_pk_bf16_f32 v39, v34, v35
	global_store_dwordx4 v[244:245], v[36:39], off offset:256
	s_waitcnt vmcnt(10)
	v_pk_add_f32 v[28:29], v[28:29], v[192:193]
	v_pk_add_f32 v[30:31], v[30:31], v[194:195]
	v_pk_add_f32 v[24:25], v[24:25], v[196:197]
	v_pk_add_f32 v[26:27], v[26:27], v[198:199]
	v_cvt_pk_bf16_f32 v28, v28, v29
	v_cvt_pk_bf16_f32 v29, v30, v31
	v_cvt_pk_bf16_f32 v30, v24, v25
	v_cvt_pk_bf16_f32 v31, v26, v27
	global_store_dwordx4 v[246:247], v[28:31], off
	v_pk_add_f32 v[20:21], v[20:21], v[200:201]
	v_pk_add_f32 v[22:23], v[22:23], v[202:203]
	v_pk_add_f32 v[16:17], v[16:17], v[204:205]
	v_pk_add_f32 v[18:19], v[18:19], v[206:207]
	v_cvt_pk_bf16_f32 v20, v20, v21
	v_cvt_pk_bf16_f32 v21, v22, v23
	v_cvt_pk_bf16_f32 v22, v16, v17
	v_cvt_pk_bf16_f32 v23, v18, v19
	global_store_dwordx4 v[246:247], v[20:23], off offset:256
	s_waitcnt vmcnt(6)
	v_pk_add_f32 v[12:13], v[12:13], v[226:227]
	v_pk_add_f32 v[14:15], v[14:15], v[228:229]
	v_pk_add_f32 v[8:9], v[8:9], v[230:231]
	v_pk_add_f32 v[10:11], v[10:11], v[232:233]
	v_cvt_pk_bf16_f32 v12, v12, v13
	v_cvt_pk_bf16_f32 v13, v14, v15
	v_cvt_pk_bf16_f32 v14, v8, v9
	v_cvt_pk_bf16_f32 v15, v10, v11
	global_store_dwordx4 v[248:249], v[12:15], off
	v_pk_add_f32 v[4:5], v[4:5], v[234:235]
	v_pk_add_f32 v[6:7], v[6:7], v[236:237]
	v_pk_add_f32 v[0:1], v[0:1], v[238:239]
	v_pk_add_f32 v[2:3], v[2:3], v[240:241]
	v_cvt_pk_bf16_f32 v4, v4, v5
	v_cvt_pk_bf16_f32 v5, v6, v7
	v_cvt_pk_bf16_f32 v6, v0, v1
	v_cvt_pk_bf16_f32 v7, v2, v3
	global_store_dwordx4 v[248:249], v[4:7], off offset:256
	s_branch .LBB0_1467
